# L2 code warm-up at seams with the window clamped to the end of the program text (no read past .text)
# speedup vs baseline: 1.0050x; 1.0021x over previous
; __device__ __forceinline__ int lane_id_() { int l; asm volatile("v_mbcnt_lo_u32_b32 %0, -1, 0\n\tv_mbcnt_hi_u32_b32 %0, -1, %0" : "=v"(l)); return l; }
; __device__ __forceinline__ unsigned xb_ld(unsigned* p)              { return __hip_atomic_load(p, __ATOMIC_RELAXED, __HIP_MEMORY_SCOPE_AGENT); }
; __device__ __forceinline__ unsigned xb_add(unsigned* p, unsigned v) { return __hip_atomic_fetch_add(p, v, __ATOMIC_RELAXED, __HIP_MEMORY_SCOPE_AGENT); }
; #define XB_SPIN(cond, bar) do { unsigned _sp = 0; while (cond) { __builtin_amdgcn_s_sleep(1); \
;     if ((++_sp & 255u) == 0u) { if (xb_ld(&(bar)[XB_TMO])) break; if (_sp > XB_SPIN_CAP) { atomicAdd(&(bar)[XB_TMO], 1u); break; } } } } while (0)
; __device__ __forceinline__ void xcd_barrier(const XcdBarrier& b, int wave_s) {
;     ...
;     if (wave_s == 0 && lane_id_() == 0) {
;         unsigned* bar = b.bar;
;         __builtin_amdgcn_s_waitcnt(0);
;         unsigned nloc = b.st[0], nx = b.st[1];
;         if (nloc == 0u) { xcd_barrier_complete(bar, b.x, nloc, nx); b.st[0] = nloc; b.st[1] = nx; }
;         const unsigned old = xb_add(&bar[XB_XSUB(b.x)], 1u);
;         const unsigned gen = old / nloc;
;         if (old + 1u == (gen + 1u) * nloc) {
;             __builtin_amdgcn_fence(__ATOMIC_RELEASE, "agent");
;             asm volatile("s_waitcnt vmcnt(0)" ::: "memory");
;             const unsigned og = xb_add(&bar[XB_TOP], 1u);
;             const unsigned tg = og / nx;
;             if (og + 1u == (tg + 1u) * nx) xb_add(&bar[XB_TOPGEN], 1u);
;             else XB_SPIN(xb_ld(&bar[XB_TOPGEN]) == tg, bar);
;             __builtin_amdgcn_fence(__ATOMIC_ACQUIRE, "agent");
;             xb_add(&bar[XB_XGEN(b.x)], 1u);
;             asm volatile("s_waitcnt vmcnt(0)" ::: "memory");
;         } else {
;             XB_SPIN(xb_ld(&bar[XB_XGEN(b.x)]) == gen, bar);
.Lpcw_S1:
	s_lshr_b32 s100, s33, 3
	s_and_b32 s100, s100, 31
	s_lshl_b32 s100, s100, 10
	s_min_u32 s100, s100, .Lcode_end-.Lpcw_S1-1024
	s_add_u32 s98, s98, s100
	s_addc_u32 s99, s99, 0
	s_mov_b64 exec, -1
	v_mbcnt_lo_u32_b32 v4, -1, 0
	v_mbcnt_hi_u32_b32 v4, -1, v4
	v_lshlrev_b32_e32 v4, 4, v4
	global_load_dwordx4 v[6:9], v4, s[98:99]
	s_mov_b64 exec, 1
	v_readfirstlane_b32 s98, v1
	s_nop 3

; __device__ __forceinline__ int lane_id_() { int l; asm volatile("v_mbcnt_lo_u32_b32 %0, -1, 0\n\tv_mbcnt_hi_u32_b32 %0, -1, %0" : "=v"(l)); return l; }
; __device__ __forceinline__ unsigned xb_ld(unsigned* p)              { return __hip_atomic_load(p, __ATOMIC_RELAXED, __HIP_MEMORY_SCOPE_AGENT); }
; __device__ __forceinline__ unsigned xb_add(unsigned* p, unsigned v) { return __hip_atomic_fetch_add(p, v, __ATOMIC_RELAXED, __HIP_MEMORY_SCOPE_AGENT); }
; #define XB_SPIN(cond, bar) do { unsigned _sp = 0; while (cond) { __builtin_amdgcn_s_sleep(1); \
;     if ((++_sp & 255u) == 0u) { if (xb_ld(&(bar)[XB_TMO])) break; if (_sp > XB_SPIN_CAP) { atomicAdd(&(bar)[XB_TMO], 1u); break; } } } } while (0)
; __device__ __forceinline__ void xcd_barrier(const XcdBarrier& b, int wave_s) {
;     ...
;     if (wave_s == 0 && lane_id_() == 0) {
;         unsigned* bar = b.bar;
;         __builtin_amdgcn_s_waitcnt(0);
;         unsigned nloc = b.st[0], nx = b.st[1];
;         if (nloc == 0u) { xcd_barrier_complete(bar, b.x, nloc, nx); b.st[0] = nloc; b.st[1] = nx; }
;         const unsigned old = xb_add(&bar[XB_XSUB(b.x)], 1u);
;         const unsigned gen = old / nloc;
;         if (old + 1u == (gen + 1u) * nloc) {
;             __builtin_amdgcn_fence(__ATOMIC_RELEASE, "agent");
;             asm volatile("s_waitcnt vmcnt(0)" ::: "memory");
;             const unsigned og = xb_add(&bar[XB_TOP], 1u);
;             const unsigned tg = og / nx;
;             if (og + 1u == (tg + 1u) * nx) xb_add(&bar[XB_TOPGEN], 1u);
;             else XB_SPIN(xb_ld(&bar[XB_TOPGEN]) == tg, bar);
;             __builtin_amdgcn_fence(__ATOMIC_ACQUIRE, "agent");
;             xb_add(&bar[XB_XGEN(b.x)], 1u);
;             asm volatile("s_waitcnt vmcnt(0)" ::: "memory");
;         } else {
;             XB_SPIN(xb_ld(&bar[XB_XGEN(b.x)]) == gen, bar);
.Lpcw_S4:
	s_lshr_b32 s100, s33, 3
	s_and_b32 s100, s100, 31
	s_lshl_b32 s100, s100, 10
	s_min_u32 s100, s100, .Lcode_end-.Lpcw_S4-1024
	s_add_u32 s98, s98, s100
	s_addc_u32 s99, s99, 0
	s_mov_b64 exec, -1
	v_mbcnt_lo_u32_b32 v4, -1, 0
	v_mbcnt_hi_u32_b32 v4, -1, v4
	v_lshlrev_b32_e32 v4, 4, v4
	global_load_dwordx4 v[6:9], v4, s[98:99]
	s_mov_b64 exec, 1
	v_readfirstlane_b32 s98, v1
	s_nop 3
	s_mov_b32 s99, 0

; __global__ void __launch_bounds__(512, 2) fwd_megakernel(Args a) {
;     ...
; }
.Lcode_end:
	.section	.rodata,"a",@progbits
	.p2align	6, 0x0
